# v28 + residual-GEMM and scale-GEMM mainloops: LDS-DMA loads in SGPR-base form (VALU address adds removed from all three generic GEMM loops)
# baseline (speedup 1.0000x reference)
; #define PG8_STAGE(bufoff, gbase, voff) do { _Pragma("unroll") for (int _i = 0; _i < 2; ++_i) \
;         __builtin_amdgcn_global_load_lds((const unsigned*)((const char*)(gbase) + (voff)[_i]), (LAS unsigned*)(lds + (bufoff) + ldsw + _i * 8192), 16, 0, 0); } while (0)
; #define PG8_LDA(dst, b, h) do { _Pragma("unroll") for (int m = 0; m < 4; ++m) _Pragma("unroll") for (int k = 0; k < 2; ++k) dst[m][k] = *(const LAS bf16x8*)(lds + PG8_SA(b, h) + aoff + m * 2048 + k * 1024); } while (0)
; #define PG8_LDB(dst, b, h) do { _Pragma("unroll") for (int n = 0; n < 2; ++n) _Pragma("unroll") for (int k = 0; k < 2; ++k) dst[n][k] = *(const LAS bf16x8*)(lds + PG8_SB(b, h) + boff + n * 2048 + k * 1024); } while (0)
; #define PG8_MMA(ai, bj, At, Bt) do { __builtin_amdgcn_s_setprio(1); _Pragma("unroll") for (int m = 0; m < 4; ++m) _Pragma("unroll") for (int n = 0; n < 2; ++n) _Pragma("unroll") for (int k = 0; k < 2; ++k) \
;         acc[ai][bj][m][n] = __builtin_amdgcn_mfma_f32_16x16x32_bf16(Bt[n][k], At[m][k], acc[ai][bj][m][n], 0, 0, 0); __builtin_amdgcn_s_setprio(0); } while (0)
; #define PG8_WAIT_V(n) asm volatile("s_waitcnt vmcnt(" #n ")" ::: "memory")
; #define PG8_WAIT_L(n) asm volatile("s_waitcnt lgkmcnt(" #n ")" ::: "memory")
; #define PG8_BAR __builtin_amdgcn_s_barrier()
; #define PG8_SCHED __builtin_amdgcn_sched_barrier(0)
; template <class Epi, class Sched>
; __device__ __forceinline__ void gemm_phase(LAS unsigned char* lds, const Gemm g, Sched S, const Epi& E) {
;     ...
;             PG8_LDB(B0, 0, 0); PG8_LDB(B1, 0, 1); PG8_SCHED; PG8_LDA(At, 0, 0); PG8_STAGE(PG8_SA(1, 1), a1 + hstepA, voffA);
;             PG8_WAIT_V(8); PG8_WAIT_L(0); PG8_BAR; PG8_MMA(0, 0, At, B0); PG8_MMA(0, 1, At, B1); PG8_BAR; PG8_SCHED;
;             PG8_LDA(At, 0, 1); PG8_STAGE(PG8_SB(0, 0), b2, voffB); PG8_STAGE(PG8_SB(0, 1), b2 + hstepB, voffB); PG8_STAGE(PG8_SA(0, 0), a2, voffA);
;             PG8_WAIT_V(8); PG8_WAIT_L(0); PG8_BAR; PG8_MMA(1, 0, At, B0); PG8_MMA(1, 1, At, B1); PG8_BAR; PG8_SCHED;
.LBB0_630:
	s_add_i32 s67, s65, 2
	s_add_u32 s2, s0, 0xfffc0080
	s_addc_u32 s3, s1, -1
	s_add_i32 s99, 0, 0x10000
	s_cmp_eq_u32 s70, s65
	s_cselect_b32 vcc_hi, s55, s3
	s_cselect_b32 vcc_lo, s54, s2
	s_cselect_b32 s77, s45, s64
	s_cselect_b32 s76, s44, s63
	s_add_i32 s65, 0, 0x14000
	v_add_u32_e32 v142, s99, v180
	v_add_u32_e32 v158, s65, v180
	ds_read_b128 v[130:133], v142
	ds_read_b128 v[134:137], v142 offset:1024
	ds_read_b128 v[138:141], v142 offset:2048
	ds_read_b128 v[142:145], v142 offset:3072
	ds_read_b128 v[146:149], v158
	ds_read_b128 v[150:153], v158 offset:1024
	ds_read_b128 v[154:157], v158 offset:2048
	ds_read_b128 v[158:161], v158 offset:3072
	s_add_i32 m0, s53, 0xc000
	ds_read_b128 v[174:177], v191
	ds_read_b128 v[192:195], v191 offset:1024
	ds_read_b128 v[196:199], v191 offset:2048
	ds_read_b128 v[200:203], v191 offset:3072
	ds_read_b128 v[204:207], v191 offset:4096
	ds_read_b128 v[208:211], v191 offset:5120
	ds_read_b128 v[212:215], v191 offset:6144
	ds_read_b128 v[216:219], v191 offset:7168
	global_load_lds_dwordx4 v172, s[0:1]
	s_add_i32 m0, s53, 0xe000
	s_nop 0
	global_load_lds_dwordx4 v170, s[0:1]
	s_waitcnt vmcnt(8)
	s_waitcnt lgkmcnt(0)
	s_barrier
	s_setprio 1
	s_waitcnt lgkmcnt(0)
	v_mfma_f32_16x16x32_bf16 v[126:129], v[130:133], v[174:177], v[126:129]
	v_mfma_f32_16x16x32_bf16 v[122:125], v[138:141], v[174:177], v[122:125]
	v_mfma_f32_16x16x32_bf16 v[114:117], v[130:133], v[196:199], v[114:117]
	v_mfma_f32_16x16x32_bf16 v[106:109], v[138:141], v[196:199], v[106:109]
	v_mfma_f32_16x16x32_bf16 v[98:101], v[130:133], v[204:207], v[98:101]
	v_mfma_f32_16x16x32_bf16 v[90:93], v[138:141], v[204:207], v[90:93]
	v_mfma_f32_16x16x32_bf16 v[82:85], v[130:133], v[212:215], v[82:85]
	v_mfma_f32_16x16x32_bf16 v[74:77], v[138:141], v[212:215], v[74:77]
	v_mfma_f32_16x16x32_bf16 v[126:129], v[134:137], v[192:195], v[126:129]
	v_mfma_f32_16x16x32_bf16 v[122:125], v[142:145], v[192:195], v[122:125]
	v_mfma_f32_16x16x32_bf16 v[114:117], v[134:137], v[200:203], v[114:117]
	v_mfma_f32_16x16x32_bf16 v[106:109], v[142:145], v[200:203], v[106:109]
	v_mfma_f32_16x16x32_bf16 v[98:101], v[134:137], v[208:211], v[98:101]
	v_mfma_f32_16x16x32_bf16 v[90:93], v[142:145], v[208:211], v[90:93]
	v_mfma_f32_16x16x32_bf16 v[82:85], v[134:137], v[216:219], v[82:85]
	v_mfma_f32_16x16x32_bf16 v[74:77], v[142:145], v[216:219], v[74:77]
	s_setprio 0
	s_setprio 1
	v_mfma_f32_16x16x32_bf16 v[118:121], v[146:149], v[174:177], v[118:121]
	v_mfma_f32_16x16x32_bf16 v[110:113], v[154:157], v[174:177], v[110:113]
	v_mfma_f32_16x16x32_bf16 v[102:105], v[146:149], v[196:199], v[102:105]
	v_mfma_f32_16x16x32_bf16 v[94:97], v[154:157], v[196:199], v[94:97]
	v_mfma_f32_16x16x32_bf16 v[86:89], v[146:149], v[204:207], v[86:89]
	v_mfma_f32_16x16x32_bf16 v[78:81], v[154:157], v[204:207], v[78:81]
	v_mfma_f32_16x16x32_bf16 v[70:73], v[146:149], v[212:215], v[70:73]
	v_mfma_f32_16x16x32_bf16 v[66:69], v[154:157], v[212:215], v[66:69]
	v_mfma_f32_16x16x32_bf16 v[118:121], v[150:153], v[192:195], v[118:121]
	v_mfma_f32_16x16x32_bf16 v[110:113], v[158:161], v[192:195], v[110:113]
	v_mfma_f32_16x16x32_bf16 v[102:105], v[150:153], v[200:203], v[102:105]
	v_mfma_f32_16x16x32_bf16 v[94:97], v[158:161], v[200:203], v[94:97]
	v_mfma_f32_16x16x32_bf16 v[86:89], v[150:153], v[208:211], v[86:89]
	v_mfma_f32_16x16x32_bf16 v[78:81], v[158:161], v[208:211], v[78:81]
	v_mfma_f32_16x16x32_bf16 v[70:73], v[150:153], v[216:219], v[70:73]
	v_mfma_f32_16x16x32_bf16 v[66:69], v[158:161], v[216:219], v[66:69]
	s_setprio 0
	s_barrier
	s_add_i32 s2, s99, s43
	s_mov_b32 m0, s2
	ds_read_b128 v[174:177], v191 offset:16384
	ds_read_b128 v[192:195], v191 offset:17408
	ds_read_b128 v[196:199], v191 offset:18432
	ds_read_b128 v[200:203], v191 offset:19456
	ds_read_b128 v[204:207], v191 offset:20480
	ds_read_b128 v[208:211], v191 offset:21504
	ds_read_b128 v[212:215], v191 offset:22528
	ds_read_b128 v[216:219], v191 offset:23552
	global_load_lds_dwordx4 v0, s[76:77]
	s_add_i32 m0, s2, 0x2000
	s_add_u32 s2, s76, 0x40000
	s_addc_u32 s3, s77, 0
	s_add_i32 s65, s65, s43
	global_load_lds_dwordx4 v168, s[76:77]
	s_mov_b32 m0, s65
	s_nop 0
	global_load_lds_dwordx4 v0, s[2:3]
	s_add_i32 m0, s65, 0x2000
	s_nop 0
	global_load_lds_dwordx4 v168, s[2:3]
	s_mov_b32 m0, s53
	s_nop 0
	global_load_lds_dwordx4 v164, vcc
	s_mov_b32 m0, s85
	s_nop 0
	global_load_lds_dwordx4 v166, vcc
	s_waitcnt vmcnt(8)
	s_waitcnt lgkmcnt(0)
	s_barrier
	s_setprio 1
	s_waitcnt lgkmcnt(0)
	v_mfma_f32_16x16x32_bf16 v[62:65], v[130:133], v[174:177], v[62:65]
	v_mfma_f32_16x16x32_bf16 v[58:61], v[138:141], v[174:177], v[58:61]
	v_mfma_f32_16x16x32_bf16 v[50:53], v[130:133], v[196:199], v[50:53]
	v_mfma_f32_16x16x32_bf16 v[42:45], v[138:141], v[196:199], v[42:45]
	v_mfma_f32_16x16x32_bf16 v[34:37], v[130:133], v[204:207], v[34:37]
	v_mfma_f32_16x16x32_bf16 v[26:29], v[138:141], v[204:207], v[26:29]
	v_mfma_f32_16x16x32_bf16 v[18:21], v[130:133], v[212:215], v[18:21]
	v_mfma_f32_16x16x32_bf16 v[10:13], v[138:141], v[212:215], v[10:13]
	v_mfma_f32_16x16x32_bf16 v[62:65], v[134:137], v[192:195], v[62:65]
	v_mfma_f32_16x16x32_bf16 v[58:61], v[142:145], v[192:195], v[58:61]
	v_mfma_f32_16x16x32_bf16 v[50:53], v[134:137], v[200:203], v[50:53]
	v_mfma_f32_16x16x32_bf16 v[42:45], v[142:145], v[200:203], v[42:45]
	v_mfma_f32_16x16x32_bf16 v[34:37], v[134:137], v[208:211], v[34:37]
	v_mfma_f32_16x16x32_bf16 v[26:29], v[142:145], v[208:211], v[26:29]
	v_mfma_f32_16x16x32_bf16 v[18:21], v[134:137], v[216:219], v[18:21]
	v_mfma_f32_16x16x32_bf16 v[10:13], v[142:145], v[216:219], v[10:13]
	s_setprio 0
	s_setprio 1
	v_mfma_f32_16x16x32_bf16 v[54:57], v[146:149], v[174:177], v[54:57]
	v_mfma_f32_16x16x32_bf16 v[46:49], v[154:157], v[174:177], v[46:49]
	v_mfma_f32_16x16x32_bf16 v[38:41], v[146:149], v[196:199], v[38:41]
	v_mfma_f32_16x16x32_bf16 v[30:33], v[154:157], v[196:199], v[30:33]
	v_mfma_f32_16x16x32_bf16 v[22:25], v[146:149], v[204:207], v[22:25]
	v_mfma_f32_16x16x32_bf16 v[14:17], v[154:157], v[204:207], v[14:17]
	v_mfma_f32_16x16x32_bf16 v[6:9], v[146:149], v[212:215], v[6:9]
	v_mfma_f32_16x16x32_bf16 v[2:5], v[154:157], v[212:215], v[2:5]
	v_mfma_f32_16x16x32_bf16 v[54:57], v[150:153], v[192:195], v[54:57]
	v_mfma_f32_16x16x32_bf16 v[46:49], v[158:161], v[192:195], v[46:49]
	v_mfma_f32_16x16x32_bf16 v[38:41], v[150:153], v[200:203], v[38:41]
	v_mfma_f32_16x16x32_bf16 v[30:33], v[158:161], v[200:203], v[30:33]
	v_mfma_f32_16x16x32_bf16 v[22:25], v[150:153], v[208:211], v[22:25]
	v_mfma_f32_16x16x32_bf16 v[14:17], v[158:161], v[208:211], v[14:17]
	v_mfma_f32_16x16x32_bf16 v[6:9], v[150:153], v[216:219], v[6:9]
	v_mfma_f32_16x16x32_bf16 v[2:5], v[158:161], v[216:219], v[2:5]
	s_setprio 0
	s_barrier
; #define PG8_STAGE(bufoff, gbase, voff) do { _Pragma("unroll") for (int _i = 0; _i < 2; ++_i) \
;         __builtin_amdgcn_global_load_lds((const unsigned*)((const char*)(gbase) + (voff)[_i]), (LAS unsigned*)(lds + (bufoff) + ldsw + _i * 8192), 16, 0, 0); } while (0)
; #define PG8_LDA(dst, b, h) do { _Pragma("unroll") for (int m = 0; m < 4; ++m) _Pragma("unroll") for (int k = 0; k < 2; ++k) dst[m][k] = *(const LAS bf16x8*)(lds + PG8_SA(b, h) + aoff + m * 2048 + k * 1024); } while (0)
; #define PG8_LDB(dst, b, h) do { _Pragma("unroll") for (int n = 0; n < 2; ++n) _Pragma("unroll") for (int k = 0; k < 2; ++k) dst[n][k] = *(const LAS bf16x8*)(lds + PG8_SB(b, h) + boff + n * 2048 + k * 1024); } while (0)
; #define PG8_MMA(ai, bj, At, Bt) do { __builtin_amdgcn_s_setprio(1); _Pragma("unroll") for (int m = 0; m < 4; ++m) _Pragma("unroll") for (int n = 0; n < 2; ++n) _Pragma("unroll") for (int k = 0; k < 2; ++k) \
;         acc[ai][bj][m][n] = __builtin_amdgcn_mfma_f32_16x16x32_bf16(Bt[n][k], At[m][k], acc[ai][bj][m][n], 0, 0, 0); __builtin_amdgcn_s_setprio(0); } while (0)
; #define PG8_WAIT_V(n) asm volatile("s_waitcnt vmcnt(" #n ")" ::: "memory")
; #define PG8_WAIT_L(n) asm volatile("s_waitcnt lgkmcnt(" #n ")" ::: "memory")
; #define PG8_BAR __builtin_amdgcn_s_barrier()
; #define PG8_SCHED __builtin_amdgcn_sched_barrier(0)
; template <class Epi, class Sched>
; __device__ __forceinline__ void gemm_phase(LAS unsigned char* lds, const Gemm g, Sched S, const Epi& E) {
;     ...
;             PG8_LDB(B0, 1, 0); PG8_LDB(B1, 1, 1); PG8_SCHED; PG8_LDA(At, 1, 0); PG8_STAGE(PG8_SA(0, 1), a2 + hstepA, voffA);
;             PG8_WAIT_V(8); PG8_WAIT_L(0); PG8_BAR; PG8_MMA(0, 0, At, B0); PG8_MMA(0, 1, At, B1); PG8_BAR; PG8_SCHED;
;             PG8_LDA(At, 1, 1); PG8_STAGE(PG8_SB(1, 0), b3, voffB); PG8_STAGE(PG8_SB(1, 1), b3 + hstepB, voffB); PG8_STAGE(PG8_SA(1, 0), a3, voffA);
;             PG8_WAIT_V(8); PG8_WAIT_L(0); PG8_BAR; PG8_MMA(1, 0, At, B0); PG8_MMA(1, 1, At, B1); PG8_BAR; PG8_SCHED;
;         }
;         if (wr == 0) PG8_BAR;
;         if (Epi::NEEDS_RS && E.ssq && has_next) {
	s_add_i32 s65, 0, 0x18000
	s_add_i32 s99, 0, 0x1c000
	v_add_u32_e32 v142, s65, v180
	v_add_u32_e32 v158, s99, v180
	ds_read_b128 v[130:133], v142
	ds_read_b128 v[134:137], v142 offset:1024
	ds_read_b128 v[138:141], v142 offset:2048
	ds_read_b128 v[142:145], v142 offset:3072
	ds_read_b128 v[146:149], v158
	ds_read_b128 v[150:153], v158 offset:1024
	ds_read_b128 v[154:157], v158 offset:2048
	ds_read_b128 v[158:161], v158 offset:3072
	s_add_u32 s2, vcc_lo, 0x40000
	s_addc_u32 s3, vcc_hi, 0
	s_mov_b32 m0, s18
	ds_read_b128 v[174:177], v191 offset:32768
	ds_read_b128 v[192:195], v191 offset:33792
	ds_read_b128 v[196:199], v191 offset:34816
	ds_read_b128 v[200:203], v191 offset:35840
	ds_read_b128 v[204:207], v191 offset:36864
	ds_read_b128 v[208:211], v191 offset:37888
	ds_read_b128 v[212:215], v191 offset:38912
	ds_read_b128 v[216:219], v191 offset:39936
	global_load_lds_dwordx4 v164, s[2:3]
	s_mov_b32 m0, s19
	s_nop 0
	global_load_lds_dwordx4 v166, s[2:3]
	s_waitcnt vmcnt(8)
	s_waitcnt lgkmcnt(0)
	s_barrier
	s_setprio 1
	s_waitcnt lgkmcnt(0)
	v_mfma_f32_16x16x32_bf16 v[126:129], v[130:133], v[174:177], v[126:129]
	v_mfma_f32_16x16x32_bf16 v[122:125], v[138:141], v[174:177], v[122:125]
	v_mfma_f32_16x16x32_bf16 v[114:117], v[130:133], v[196:199], v[114:117]
	v_mfma_f32_16x16x32_bf16 v[106:109], v[138:141], v[196:199], v[106:109]
	v_mfma_f32_16x16x32_bf16 v[98:101], v[130:133], v[204:207], v[98:101]
	v_mfma_f32_16x16x32_bf16 v[90:93], v[138:141], v[204:207], v[90:93]
	v_mfma_f32_16x16x32_bf16 v[82:85], v[130:133], v[212:215], v[82:85]
	v_mfma_f32_16x16x32_bf16 v[74:77], v[138:141], v[212:215], v[74:77]
	v_mfma_f32_16x16x32_bf16 v[126:129], v[134:137], v[192:195], v[126:129]
	v_mfma_f32_16x16x32_bf16 v[122:125], v[142:145], v[192:195], v[122:125]
	v_mfma_f32_16x16x32_bf16 v[114:117], v[134:137], v[200:203], v[114:117]
	v_mfma_f32_16x16x32_bf16 v[106:109], v[142:145], v[200:203], v[106:109]
	v_mfma_f32_16x16x32_bf16 v[98:101], v[134:137], v[208:211], v[98:101]
	v_mfma_f32_16x16x32_bf16 v[90:93], v[142:145], v[208:211], v[90:93]
	v_mfma_f32_16x16x32_bf16 v[82:85], v[134:137], v[216:219], v[82:85]
	v_mfma_f32_16x16x32_bf16 v[74:77], v[142:145], v[216:219], v[74:77]
	s_setprio 0
	s_setprio 1
	v_mfma_f32_16x16x32_bf16 v[118:121], v[146:149], v[174:177], v[118:121]
	v_mfma_f32_16x16x32_bf16 v[110:113], v[154:157], v[174:177], v[110:113]
	v_mfma_f32_16x16x32_bf16 v[102:105], v[146:149], v[196:199], v[102:105]
	v_mfma_f32_16x16x32_bf16 v[94:97], v[154:157], v[196:199], v[94:97]
	v_mfma_f32_16x16x32_bf16 v[86:89], v[146:149], v[204:207], v[86:89]
	v_mfma_f32_16x16x32_bf16 v[78:81], v[154:157], v[204:207], v[78:81]
	v_mfma_f32_16x16x32_bf16 v[70:73], v[146:149], v[212:215], v[70:73]
	v_mfma_f32_16x16x32_bf16 v[66:69], v[154:157], v[212:215], v[66:69]
	v_mfma_f32_16x16x32_bf16 v[118:121], v[150:153], v[192:195], v[118:121]
	v_mfma_f32_16x16x32_bf16 v[110:113], v[158:161], v[192:195], v[110:113]
	v_mfma_f32_16x16x32_bf16 v[102:105], v[150:153], v[200:203], v[102:105]
	v_mfma_f32_16x16x32_bf16 v[94:97], v[158:161], v[200:203], v[94:97]
	v_mfma_f32_16x16x32_bf16 v[86:89], v[150:153], v[208:211], v[86:89]
	v_mfma_f32_16x16x32_bf16 v[78:81], v[158:161], v[208:211], v[78:81]
	v_mfma_f32_16x16x32_bf16 v[70:73], v[150:153], v[216:219], v[70:73]
	v_mfma_f32_16x16x32_bf16 v[66:69], v[158:161], v[216:219], v[66:69]
	s_setprio 0
	s_barrier
	s_add_i32 s2, s65, s43
	s_add_u32 s100, s76, 0x80
	s_addc_u32 s101, s77, 0
	s_mov_b32 m0, s2
	ds_read_b128 v[174:177], v191 offset:49152
	ds_read_b128 v[192:195], v191 offset:50176
	ds_read_b128 v[196:199], v191 offset:51200
	ds_read_b128 v[200:203], v191 offset:52224
	ds_read_b128 v[204:207], v191 offset:53248
	ds_read_b128 v[208:211], v191 offset:54272
	ds_read_b128 v[212:215], v191 offset:55296
	ds_read_b128 v[216:219], v191 offset:56320
	global_load_lds_dwordx4 v0, s[100:101]
	s_add_i32 m0, s2, 0x2000
	s_add_u32 s2, s76, 0x40080
	s_addc_u32 s3, s77, 0
	s_add_i32 s65, s99, s43
	global_load_lds_dwordx4 v168, s[100:101]
	s_mov_b32 m0, s65
	s_nop 0
	global_load_lds_dwordx4 v0, s[2:3]
	s_add_i32 m0, s65, 0x2000
	s_nop 0
	global_load_lds_dwordx4 v168, s[2:3]
	s_add_u32 s100, vcc_lo, 0x80
	s_addc_u32 s101, vcc_hi, 0
	s_mov_b32 m0, s71
	s_nop 0
	global_load_lds_dwordx4 v164, s[100:101]
	s_mov_b32 m0, s40
	s_nop 0
	global_load_lds_dwordx4 v166, s[100:101]
	s_waitcnt vmcnt(8)
	s_waitcnt lgkmcnt(0)
	s_barrier
	s_setprio 1
	s_waitcnt lgkmcnt(0)
	v_mfma_f32_16x16x32_bf16 v[62:65], v[130:133], v[174:177], v[62:65]
	v_mfma_f32_16x16x32_bf16 v[58:61], v[138:141], v[174:177], v[58:61]
	v_mfma_f32_16x16x32_bf16 v[50:53], v[130:133], v[196:199], v[50:53]
	v_mfma_f32_16x16x32_bf16 v[42:45], v[138:141], v[196:199], v[42:45]
	v_mfma_f32_16x16x32_bf16 v[34:37], v[130:133], v[204:207], v[34:37]
	v_mfma_f32_16x16x32_bf16 v[26:29], v[138:141], v[204:207], v[26:29]
	v_mfma_f32_16x16x32_bf16 v[18:21], v[130:133], v[212:215], v[18:21]
	v_mfma_f32_16x16x32_bf16 v[10:13], v[138:141], v[212:215], v[10:13]
	v_mfma_f32_16x16x32_bf16 v[62:65], v[134:137], v[192:195], v[62:65]
	v_mfma_f32_16x16x32_bf16 v[58:61], v[142:145], v[192:195], v[58:61]
	v_mfma_f32_16x16x32_bf16 v[50:53], v[134:137], v[200:203], v[50:53]
	v_mfma_f32_16x16x32_bf16 v[42:45], v[142:145], v[200:203], v[42:45]
	v_mfma_f32_16x16x32_bf16 v[34:37], v[134:137], v[208:211], v[34:37]
	v_mfma_f32_16x16x32_bf16 v[26:29], v[142:145], v[208:211], v[26:29]
	v_mfma_f32_16x16x32_bf16 v[18:21], v[134:137], v[216:219], v[18:21]
	v_mfma_f32_16x16x32_bf16 v[10:13], v[142:145], v[216:219], v[10:13]
	s_setprio 0
	s_setprio 1
	v_mfma_f32_16x16x32_bf16 v[54:57], v[146:149], v[174:177], v[54:57]
	v_mfma_f32_16x16x32_bf16 v[46:49], v[154:157], v[174:177], v[46:49]
	v_mfma_f32_16x16x32_bf16 v[38:41], v[146:149], v[196:199], v[38:41]
	v_mfma_f32_16x16x32_bf16 v[30:33], v[154:157], v[196:199], v[30:33]
	v_mfma_f32_16x16x32_bf16 v[22:25], v[146:149], v[204:207], v[22:25]
	v_mfma_f32_16x16x32_bf16 v[14:17], v[154:157], v[204:207], v[14:17]
	v_mfma_f32_16x16x32_bf16 v[6:9], v[146:149], v[212:215], v[6:9]
	v_mfma_f32_16x16x32_bf16 v[2:5], v[154:157], v[212:215], v[2:5]
	v_mfma_f32_16x16x32_bf16 v[54:57], v[150:153], v[192:195], v[54:57]
	v_mfma_f32_16x16x32_bf16 v[46:49], v[158:161], v[192:195], v[46:49]
	v_mfma_f32_16x16x32_bf16 v[38:41], v[150:153], v[200:203], v[38:41]
	v_mfma_f32_16x16x32_bf16 v[30:33], v[158:161], v[200:203], v[30:33]
	v_mfma_f32_16x16x32_bf16 v[22:25], v[150:153], v[208:211], v[22:25]
	v_mfma_f32_16x16x32_bf16 v[14:17], v[158:161], v[208:211], v[14:17]
	v_mfma_f32_16x16x32_bf16 v[6:9], v[150:153], v[216:219], v[6:9]
	v_mfma_f32_16x16x32_bf16 v[2:5], v[158:161], v[216:219], v[2:5]
	s_setprio 0
	s_barrier
	s_add_u32 s63, s63, 0x100
	s_addc_u32 s64, s64, 0
	s_add_u32 s0, s0, 0x100
	s_addc_u32 s1, s1, 0
	s_cmp_ge_u32 s67, s58
	s_mov_b32 s65, s67
	s_cbranch_scc0 .LBB0_630
	s_and_b64 vcc, exec, s[94:95]
	s_cbranch_vccz .LBB0_635
	s_barrier
	s_and_b64 s[0:1], s[96:97], s[10:11]
	s_andn2_b64 vcc, exec, s[0:1]
	s_mov_b64 s[0:1], -1
	s_cbranch_vccnz .LBB0_636

; #define PG8_STAGE(bufoff, gbase, voff) do { _Pragma("unroll") for (int _i = 0; _i < 2; ++_i) \
;         __builtin_amdgcn_global_load_lds((const unsigned*)((const char*)(gbase) + (voff)[_i]), (LAS unsigned*)(lds + (bufoff) + ldsw + _i * 8192), 16, 0, 0); } while (0)
; #define PG8_LDA(dst, b, h) do { _Pragma("unroll") for (int m = 0; m < 4; ++m) _Pragma("unroll") for (int k = 0; k < 2; ++k) dst[m][k] = *(const LAS bf16x8*)(lds + PG8_SA(b, h) + aoff + m * 2048 + k * 1024); } while (0)
; #define PG8_LDB(dst, b, h) do { _Pragma("unroll") for (int n = 0; n < 2; ++n) _Pragma("unroll") for (int k = 0; k < 2; ++k) dst[n][k] = *(const LAS bf16x8*)(lds + PG8_SB(b, h) + boff + n * 2048 + k * 1024); } while (0)
; #define PG8_MMA(ai, bj, At, Bt) do { __builtin_amdgcn_s_setprio(1); _Pragma("unroll") for (int m = 0; m < 4; ++m) _Pragma("unroll") for (int n = 0; n < 2; ++n) _Pragma("unroll") for (int k = 0; k < 2; ++k) \
;         acc[ai][bj][m][n] = __builtin_amdgcn_mfma_f32_16x16x32_bf16(Bt[n][k], At[m][k], acc[ai][bj][m][n], 0, 0, 0); __builtin_amdgcn_s_setprio(0); } while (0)
; #define PG8_WAIT_V(n) asm volatile("s_waitcnt vmcnt(" #n ")" ::: "memory")
; #define PG8_WAIT_L(n) asm volatile("s_waitcnt lgkmcnt(" #n ")" ::: "memory")
; #define PG8_BAR __builtin_amdgcn_s_barrier()
; #define PG8_SCHED __builtin_amdgcn_sched_barrier(0)
; template <class Epi, class Sched>
; __device__ __forceinline__ void gemm_phase(LAS unsigned char* lds, const Gemm g, Sched S, const Epi& E) {
;     ...
;             const bool last = (t == nt - 2);
;             const char* a1 = cA + (size_t)(t + 1) * kstep;
;             const char* a2 = last ? nA : cA + (size_t)(t + 2) * kstep; const char* b2 = last ? nB : cB + (size_t)(t + 2) * kstep;
;             const char* a3 = a2 + kstep; const char* b3 = b2 + kstep;
;             PG8_LDB(B0, 0, 0); PG8_LDB(B1, 0, 1); PG8_SCHED; PG8_LDA(At, 0, 0); PG8_STAGE(PG8_SA(1, 1), a1 + hstepA, voffA);
;             PG8_WAIT_V(8); PG8_WAIT_L(0); PG8_BAR; PG8_MMA(0, 0, At, B0); PG8_MMA(0, 1, At, B1); PG8_BAR; PG8_SCHED;
;             PG8_LDA(At, 0, 1); PG8_STAGE(PG8_SB(0, 0), b2, voffB); PG8_STAGE(PG8_SB(0, 1), b2 + hstepB, voffB); PG8_STAGE(PG8_SA(0, 0), a2, voffA);
;             PG8_WAIT_V(8); PG8_WAIT_L(0); PG8_BAR; PG8_MMA(1, 0, At, B0); PG8_MMA(1, 1, At, B1); PG8_BAR; PG8_SCHED;
.LBB0_727:
	s_add_i32 s21, s20, 2
	s_add_u32 s3, s42, 0x80
	s_addc_u32 s35, s43, 0
	s_add_i32 s52, 0, 0x10000
	s_cmp_eq_u32 s99, s20
	s_cselect_b32 s45, s89, s35
	s_cselect_b32 s44, s88, s3
	s_cselect_b32 s41, s91, s19
	s_cselect_b32 s40, s90, s11
	s_add_i32 s3, 0, 0x14000
	v_add_u32_e32 v126, s52, v192
	v_add_u32_e32 v170, s3, v192
	ds_read_b128 v[114:117], v126
	ds_read_b128 v[118:121], v126 offset:1024
	ds_read_b128 v[122:125], v126 offset:2048
	ds_read_b128 v[126:129], v126 offset:3072
	ds_read_b128 v[130:133], v170
	ds_read_b128 v[134:137], v170 offset:1024
	ds_read_b128 v[166:169], v170 offset:2048
	ds_read_b128 v[170:173], v170 offset:3072
	s_add_i32 m0, s85, 0xc000
	ds_read_b128 v[174:177], v194
	ds_read_b128 v[178:181], v194 offset:1024
	ds_read_b128 v[196:199], v194 offset:2048
	ds_read_b128 v[200:203], v194 offset:3072
	ds_read_b128 v[204:207], v194 offset:4096
	ds_read_b128 v[208:211], v194 offset:5120
	ds_read_b128 v[212:215], v194 offset:6144
	ds_read_b128 v[216:219], v194 offset:7168
	global_load_lds_dwordx4 v164, s[42:43]
	s_add_i32 m0, s85, 0xe000
	s_nop 0
	global_load_lds_dwordx4 v160, s[42:43]
	s_waitcnt vmcnt(8)
	s_waitcnt lgkmcnt(0)
	s_barrier
	s_setprio 1
	s_waitcnt lgkmcnt(0)
	v_mfma_f32_16x16x32_bf16 v[150:153], v[114:117], v[174:177], v[150:153]
	v_mfma_f32_16x16x32_bf16 v[146:149], v[122:125], v[174:177], v[146:149]
	v_mfma_f32_16x16x32_bf16 v[110:113], v[114:117], v[196:199], v[110:113]
	v_mfma_f32_16x16x32_bf16 v[106:109], v[122:125], v[196:199], v[106:109]
	v_mfma_f32_16x16x32_bf16 v[94:97], v[114:117], v[204:207], v[94:97]
	v_mfma_f32_16x16x32_bf16 v[90:93], v[122:125], v[204:207], v[90:93]
	v_mfma_f32_16x16x32_bf16 v[78:81], v[114:117], v[212:215], v[78:81]
	v_mfma_f32_16x16x32_bf16 v[74:77], v[122:125], v[212:215], v[74:77]
	v_mfma_f32_16x16x32_bf16 v[150:153], v[118:121], v[178:181], v[150:153]
	v_mfma_f32_16x16x32_bf16 v[146:149], v[126:129], v[178:181], v[146:149]
	v_mfma_f32_16x16x32_bf16 v[110:113], v[118:121], v[200:203], v[110:113]
	v_mfma_f32_16x16x32_bf16 v[106:109], v[126:129], v[200:203], v[106:109]
	v_mfma_f32_16x16x32_bf16 v[94:97], v[118:121], v[208:211], v[94:97]
	v_mfma_f32_16x16x32_bf16 v[90:93], v[126:129], v[208:211], v[90:93]
	v_mfma_f32_16x16x32_bf16 v[78:81], v[118:121], v[216:219], v[78:81]
	v_mfma_f32_16x16x32_bf16 v[74:77], v[126:129], v[216:219], v[74:77]
	s_setprio 0
	s_setprio 1
	v_mfma_f32_16x16x32_bf16 v[142:145], v[130:133], v[174:177], v[142:145]
	v_mfma_f32_16x16x32_bf16 v[138:141], v[166:169], v[174:177], v[138:141]
	v_mfma_f32_16x16x32_bf16 v[102:105], v[130:133], v[196:199], v[102:105]
	v_mfma_f32_16x16x32_bf16 v[98:101], v[166:169], v[196:199], v[98:101]
	v_mfma_f32_16x16x32_bf16 v[86:89], v[130:133], v[204:207], v[86:89]
	v_mfma_f32_16x16x32_bf16 v[82:85], v[166:169], v[204:207], v[82:85]
	v_mfma_f32_16x16x32_bf16 v[70:73], v[130:133], v[212:215], v[70:73]
	v_mfma_f32_16x16x32_bf16 v[66:69], v[166:169], v[212:215], v[66:69]
	v_mfma_f32_16x16x32_bf16 v[142:145], v[134:137], v[178:181], v[142:145]
	v_mfma_f32_16x16x32_bf16 v[138:141], v[170:173], v[178:181], v[138:141]
	v_mfma_f32_16x16x32_bf16 v[102:105], v[134:137], v[200:203], v[102:105]
	v_mfma_f32_16x16x32_bf16 v[98:101], v[170:173], v[200:203], v[98:101]
	v_mfma_f32_16x16x32_bf16 v[86:89], v[134:137], v[208:211], v[86:89]
	v_mfma_f32_16x16x32_bf16 v[82:85], v[170:173], v[208:211], v[82:85]
	v_mfma_f32_16x16x32_bf16 v[70:73], v[134:137], v[216:219], v[70:73]
	v_mfma_f32_16x16x32_bf16 v[66:69], v[170:173], v[216:219], v[66:69]
	s_setprio 0
	s_barrier
	s_add_i32 s20, s52, s77
	s_add_u32 s100, s40, 0x80
	s_addc_u32 s101, s41, 0
	s_mov_b32 m0, s20
	ds_read_b128 v[174:177], v194 offset:16384
	ds_read_b128 v[178:181], v194 offset:17408
	ds_read_b128 v[196:199], v194 offset:18432
	ds_read_b128 v[200:203], v194 offset:19456
	ds_read_b128 v[204:207], v194 offset:20480
	ds_read_b128 v[208:211], v194 offset:21504
	ds_read_b128 v[212:215], v194 offset:22528
	ds_read_b128 v[216:219], v194 offset:23552
	global_load_lds_dwordx4 v0, s[40:41]
	s_add_i32 m0, s20, 0x2000
	s_add_i32 s3, s3, s77
	global_load_lds_dwordx4 v158, s[40:41]
	s_add_u32 s40, s40, s24
	s_addc_u32 s41, s41, s25
	s_mov_b32 m0, s3
	s_nop 0
	global_load_lds_dwordx4 v0, s[40:41]
	s_add_i32 m0, s3, 0x2000
	s_nop 0
	global_load_lds_dwordx4 v158, s[40:41]
	s_mov_b32 m0, s85
	s_nop 0
	global_load_lds_dwordx4 v154, s[44:45]
	s_mov_b32 m0, s92
	s_nop 0
	global_load_lds_dwordx4 v156, s[44:45]
	s_waitcnt vmcnt(8)
	s_waitcnt lgkmcnt(0)
	s_barrier
	s_setprio 1
	s_waitcnt lgkmcnt(0)
	v_mfma_f32_16x16x32_bf16 v[62:65], v[114:117], v[174:177], v[62:65]
	v_mfma_f32_16x16x32_bf16 v[58:61], v[122:125], v[174:177], v[58:61]
	v_mfma_f32_16x16x32_bf16 v[46:49], v[114:117], v[196:199], v[46:49]
	v_mfma_f32_16x16x32_bf16 v[42:45], v[122:125], v[196:199], v[42:45]
	v_mfma_f32_16x16x32_bf16 v[30:33], v[114:117], v[204:207], v[30:33]
	v_mfma_f32_16x16x32_bf16 v[26:29], v[122:125], v[204:207], v[26:29]
	v_mfma_f32_16x16x32_bf16 v[14:17], v[114:117], v[212:215], v[14:17]
	v_mfma_f32_16x16x32_bf16 v[10:13], v[122:125], v[212:215], v[10:13]
	v_mfma_f32_16x16x32_bf16 v[62:65], v[118:121], v[178:181], v[62:65]
	v_mfma_f32_16x16x32_bf16 v[58:61], v[126:129], v[178:181], v[58:61]
	v_mfma_f32_16x16x32_bf16 v[46:49], v[118:121], v[200:203], v[46:49]
	v_mfma_f32_16x16x32_bf16 v[42:45], v[126:129], v[200:203], v[42:45]
	v_mfma_f32_16x16x32_bf16 v[30:33], v[118:121], v[208:211], v[30:33]
	v_mfma_f32_16x16x32_bf16 v[26:29], v[126:129], v[208:211], v[26:29]
	v_mfma_f32_16x16x32_bf16 v[14:17], v[118:121], v[216:219], v[14:17]
	v_mfma_f32_16x16x32_bf16 v[10:13], v[126:129], v[216:219], v[10:13]
	s_setprio 0
	s_setprio 1
	v_mfma_f32_16x16x32_bf16 v[54:57], v[130:133], v[174:177], v[54:57]
	v_mfma_f32_16x16x32_bf16 v[50:53], v[166:169], v[174:177], v[50:53]
	v_mfma_f32_16x16x32_bf16 v[38:41], v[130:133], v[196:199], v[38:41]
	v_mfma_f32_16x16x32_bf16 v[34:37], v[166:169], v[196:199], v[34:37]
	v_mfma_f32_16x16x32_bf16 v[22:25], v[130:133], v[204:207], v[22:25]
	v_mfma_f32_16x16x32_bf16 v[18:21], v[166:169], v[204:207], v[18:21]
	v_mfma_f32_16x16x32_bf16 v[6:9], v[130:133], v[212:215], v[6:9]
	v_mfma_f32_16x16x32_bf16 v[2:5], v[166:169], v[212:215], v[2:5]
	v_mfma_f32_16x16x32_bf16 v[54:57], v[134:137], v[178:181], v[54:57]
	v_mfma_f32_16x16x32_bf16 v[50:53], v[170:173], v[178:181], v[50:53]
	v_mfma_f32_16x16x32_bf16 v[38:41], v[134:137], v[200:203], v[38:41]
	v_mfma_f32_16x16x32_bf16 v[34:37], v[170:173], v[200:203], v[34:37]
	v_mfma_f32_16x16x32_bf16 v[22:25], v[134:137], v[208:211], v[22:25]
	v_mfma_f32_16x16x32_bf16 v[18:21], v[170:173], v[208:211], v[18:21]
	v_mfma_f32_16x16x32_bf16 v[6:9], v[134:137], v[216:219], v[6:9]
	v_mfma_f32_16x16x32_bf16 v[2:5], v[170:173], v[216:219], v[2:5]
	s_setprio 0
	s_barrier
; #define PG8_STAGE(bufoff, gbase, voff) do { _Pragma("unroll") for (int _i = 0; _i < 2; ++_i) \
;         __builtin_amdgcn_global_load_lds((const unsigned*)((const char*)(gbase) + (voff)[_i]), (LAS unsigned*)(lds + (bufoff) + ldsw + _i * 8192), 16, 0, 0); } while (0)
; #define PG8_LDA(dst, b, h) do { _Pragma("unroll") for (int m = 0; m < 4; ++m) _Pragma("unroll") for (int k = 0; k < 2; ++k) dst[m][k] = *(const LAS bf16x8*)(lds + PG8_SA(b, h) + aoff + m * 2048 + k * 1024); } while (0)
; #define PG8_LDB(dst, b, h) do { _Pragma("unroll") for (int n = 0; n < 2; ++n) _Pragma("unroll") for (int k = 0; k < 2; ++k) dst[n][k] = *(const LAS bf16x8*)(lds + PG8_SB(b, h) + boff + n * 2048 + k * 1024); } while (0)
; #define PG8_MMA(ai, bj, At, Bt) do { __builtin_amdgcn_s_setprio(1); _Pragma("unroll") for (int m = 0; m < 4; ++m) _Pragma("unroll") for (int n = 0; n < 2; ++n) _Pragma("unroll") for (int k = 0; k < 2; ++k) \
;         acc[ai][bj][m][n] = __builtin_amdgcn_mfma_f32_16x16x32_bf16(Bt[n][k], At[m][k], acc[ai][bj][m][n], 0, 0, 0); __builtin_amdgcn_s_setprio(0); } while (0)
; #define PG8_WAIT_V(n) asm volatile("s_waitcnt vmcnt(" #n ")" ::: "memory")
; #define PG8_WAIT_L(n) asm volatile("s_waitcnt lgkmcnt(" #n ")" ::: "memory")
; #define PG8_BAR __builtin_amdgcn_s_barrier()
; #define PG8_SCHED __builtin_amdgcn_sched_barrier(0)
; template <class Epi, class Sched>
; __device__ __forceinline__ void gemm_phase(LAS unsigned char* lds, const Gemm g, Sched S, const Epi& E) {
;     ...
;             PG8_LDB(B0, 1, 0); PG8_LDB(B1, 1, 1); PG8_SCHED; PG8_LDA(At, 1, 0); PG8_STAGE(PG8_SA(0, 1), a2 + hstepA, voffA);
;             PG8_WAIT_V(8); PG8_WAIT_L(0); PG8_BAR; PG8_MMA(0, 0, At, B0); PG8_MMA(0, 1, At, B1); PG8_BAR; PG8_SCHED;
;             PG8_LDA(At, 1, 1); PG8_STAGE(PG8_SB(1, 0), b3, voffB); PG8_STAGE(PG8_SB(1, 1), b3 + hstepB, voffB); PG8_STAGE(PG8_SA(1, 0), a3, voffA);
;             PG8_WAIT_V(8); PG8_WAIT_L(0); PG8_BAR; PG8_MMA(1, 0, At, B0); PG8_MMA(1, 1, At, B1); PG8_BAR; PG8_SCHED;
;         }
;         if (wr == 0) PG8_BAR;
;         if (Epi::NEEDS_RS && E.ssq && has_next) {
	s_add_i32 s3, 0, 0x18000
	s_add_i32 s20, 0, 0x1c000
	v_add_u32_e32 v126, s3, v192
	v_add_u32_e32 v170, s20, v192
	ds_read_b128 v[114:117], v126
	ds_read_b128 v[118:121], v126 offset:1024
	ds_read_b128 v[122:125], v126 offset:2048
	ds_read_b128 v[126:129], v126 offset:3072
	ds_read_b128 v[130:133], v170
	ds_read_b128 v[134:137], v170 offset:1024
	ds_read_b128 v[166:169], v170 offset:2048
	ds_read_b128 v[170:173], v170 offset:3072
	s_add_u32 s40, s44, s8
	s_addc_u32 s41, s45, 0
	s_mov_b32 m0, s93
	ds_read_b128 v[174:177], v194 offset:32768
	ds_read_b128 v[178:181], v194 offset:33792
	ds_read_b128 v[196:199], v194 offset:34816
	ds_read_b128 v[200:203], v194 offset:35840
	ds_read_b128 v[204:207], v194 offset:36864
	ds_read_b128 v[208:211], v194 offset:37888
	ds_read_b128 v[212:215], v194 offset:38912
	ds_read_b128 v[216:219], v194 offset:39936
	global_load_lds_dwordx4 v154, s[40:41]
	s_mov_b32 m0, s94
	s_nop 0
	global_load_lds_dwordx4 v156, s[40:41]
	s_waitcnt vmcnt(8)
	s_waitcnt lgkmcnt(0)
	s_barrier
	s_setprio 1
	s_waitcnt lgkmcnt(0)
	v_mfma_f32_16x16x32_bf16 v[150:153], v[114:117], v[174:177], v[150:153]
	v_mfma_f32_16x16x32_bf16 v[146:149], v[122:125], v[174:177], v[146:149]
	v_mfma_f32_16x16x32_bf16 v[110:113], v[114:117], v[196:199], v[110:113]
	v_mfma_f32_16x16x32_bf16 v[106:109], v[122:125], v[196:199], v[106:109]
	v_mfma_f32_16x16x32_bf16 v[94:97], v[114:117], v[204:207], v[94:97]
	v_mfma_f32_16x16x32_bf16 v[90:93], v[122:125], v[204:207], v[90:93]
	v_mfma_f32_16x16x32_bf16 v[78:81], v[114:117], v[212:215], v[78:81]
	v_mfma_f32_16x16x32_bf16 v[74:77], v[122:125], v[212:215], v[74:77]
	v_mfma_f32_16x16x32_bf16 v[150:153], v[118:121], v[178:181], v[150:153]
	v_mfma_f32_16x16x32_bf16 v[146:149], v[126:129], v[178:181], v[146:149]
	v_mfma_f32_16x16x32_bf16 v[110:113], v[118:121], v[200:203], v[110:113]
	v_mfma_f32_16x16x32_bf16 v[106:109], v[126:129], v[200:203], v[106:109]
	v_mfma_f32_16x16x32_bf16 v[94:97], v[118:121], v[208:211], v[94:97]
	v_mfma_f32_16x16x32_bf16 v[90:93], v[126:129], v[208:211], v[90:93]
	v_mfma_f32_16x16x32_bf16 v[78:81], v[118:121], v[216:219], v[78:81]
	v_mfma_f32_16x16x32_bf16 v[74:77], v[126:129], v[216:219], v[74:77]
	s_setprio 0
	s_setprio 1
	v_mfma_f32_16x16x32_bf16 v[142:145], v[130:133], v[174:177], v[142:145]
	v_mfma_f32_16x16x32_bf16 v[138:141], v[166:169], v[174:177], v[138:141]
	v_mfma_f32_16x16x32_bf16 v[102:105], v[130:133], v[196:199], v[102:105]
	v_mfma_f32_16x16x32_bf16 v[98:101], v[166:169], v[196:199], v[98:101]
	v_mfma_f32_16x16x32_bf16 v[86:89], v[130:133], v[204:207], v[86:89]
	v_mfma_f32_16x16x32_bf16 v[82:85], v[166:169], v[204:207], v[82:85]
	v_mfma_f32_16x16x32_bf16 v[70:73], v[130:133], v[212:215], v[70:73]
	v_mfma_f32_16x16x32_bf16 v[66:69], v[166:169], v[212:215], v[66:69]
	v_mfma_f32_16x16x32_bf16 v[142:145], v[134:137], v[178:181], v[142:145]
	v_mfma_f32_16x16x32_bf16 v[138:141], v[170:173], v[178:181], v[138:141]
	v_mfma_f32_16x16x32_bf16 v[102:105], v[134:137], v[200:203], v[102:105]
	v_mfma_f32_16x16x32_bf16 v[98:101], v[170:173], v[200:203], v[98:101]
	v_mfma_f32_16x16x32_bf16 v[86:89], v[134:137], v[208:211], v[86:89]
	v_mfma_f32_16x16x32_bf16 v[82:85], v[170:173], v[208:211], v[82:85]
	v_mfma_f32_16x16x32_bf16 v[70:73], v[134:137], v[216:219], v[70:73]
	v_mfma_f32_16x16x32_bf16 v[66:69], v[170:173], v[216:219], v[66:69]
	s_setprio 0
	s_barrier
	s_add_i32 s3, s3, s77
	s_mov_b32 m0, s3
	ds_read_b128 v[174:177], v194 offset:49152
	ds_read_b128 v[178:181], v194 offset:50176
	ds_read_b128 v[196:199], v194 offset:51200
	ds_read_b128 v[200:203], v194 offset:52224
	ds_read_b128 v[204:207], v194 offset:53248
	ds_read_b128 v[208:211], v194 offset:54272
	ds_read_b128 v[212:215], v194 offset:55296
	ds_read_b128 v[216:219], v194 offset:56320
	global_load_lds_dwordx4 v0, s[100:101]
	s_add_i32 m0, s3, 0x2000
	s_add_i32 s3, s20, s77
	global_load_lds_dwordx4 v158, s[100:101]
	s_add_u32 s100, s100, s24
	s_addc_u32 s101, s101, s25
	s_mov_b32 m0, s3
	s_nop 0
	global_load_lds_dwordx4 v0, s[100:101]
	s_add_i32 m0, s3, 0x2000
	s_nop 0
	global_load_lds_dwordx4 v158, s[100:101]
	s_add_u32 s100, s44, 0x80
	s_addc_u32 s101, s45, 0
	s_mov_b32 m0, s97
	s_nop 0
	global_load_lds_dwordx4 v154, s[100:101]
	s_mov_b32 m0, s98
	s_nop 0
	global_load_lds_dwordx4 v156, s[100:101]
	s_waitcnt vmcnt(8)
	s_waitcnt lgkmcnt(0)
	s_barrier
	s_setprio 1
	s_waitcnt lgkmcnt(0)
	v_mfma_f32_16x16x32_bf16 v[62:65], v[114:117], v[174:177], v[62:65]
	v_mfma_f32_16x16x32_bf16 v[58:61], v[122:125], v[174:177], v[58:61]
	v_mfma_f32_16x16x32_bf16 v[46:49], v[114:117], v[196:199], v[46:49]
	v_mfma_f32_16x16x32_bf16 v[42:45], v[122:125], v[196:199], v[42:45]
	v_mfma_f32_16x16x32_bf16 v[30:33], v[114:117], v[204:207], v[30:33]
	v_mfma_f32_16x16x32_bf16 v[26:29], v[122:125], v[204:207], v[26:29]
	v_mfma_f32_16x16x32_bf16 v[14:17], v[114:117], v[212:215], v[14:17]
	v_mfma_f32_16x16x32_bf16 v[10:13], v[122:125], v[212:215], v[10:13]
	v_mfma_f32_16x16x32_bf16 v[62:65], v[118:121], v[178:181], v[62:65]
	v_mfma_f32_16x16x32_bf16 v[58:61], v[126:129], v[178:181], v[58:61]
	v_mfma_f32_16x16x32_bf16 v[46:49], v[118:121], v[200:203], v[46:49]
	v_mfma_f32_16x16x32_bf16 v[42:45], v[126:129], v[200:203], v[42:45]
	v_mfma_f32_16x16x32_bf16 v[30:33], v[118:121], v[208:211], v[30:33]
	v_mfma_f32_16x16x32_bf16 v[26:29], v[126:129], v[208:211], v[26:29]
	v_mfma_f32_16x16x32_bf16 v[14:17], v[118:121], v[216:219], v[14:17]
	v_mfma_f32_16x16x32_bf16 v[10:13], v[126:129], v[216:219], v[10:13]
	s_setprio 0
	s_setprio 1
	v_mfma_f32_16x16x32_bf16 v[54:57], v[130:133], v[174:177], v[54:57]
	v_mfma_f32_16x16x32_bf16 v[50:53], v[166:169], v[174:177], v[50:53]
	v_mfma_f32_16x16x32_bf16 v[38:41], v[130:133], v[196:199], v[38:41]
	v_mfma_f32_16x16x32_bf16 v[34:37], v[166:169], v[196:199], v[34:37]
	v_mfma_f32_16x16x32_bf16 v[22:25], v[130:133], v[204:207], v[22:25]
	v_mfma_f32_16x16x32_bf16 v[18:21], v[166:169], v[204:207], v[18:21]
	v_mfma_f32_16x16x32_bf16 v[6:9], v[130:133], v[212:215], v[6:9]
	v_mfma_f32_16x16x32_bf16 v[2:5], v[166:169], v[212:215], v[2:5]
	v_mfma_f32_16x16x32_bf16 v[54:57], v[134:137], v[178:181], v[54:57]
	v_mfma_f32_16x16x32_bf16 v[50:53], v[170:173], v[178:181], v[50:53]
	v_mfma_f32_16x16x32_bf16 v[38:41], v[134:137], v[200:203], v[38:41]
	v_mfma_f32_16x16x32_bf16 v[34:37], v[170:173], v[200:203], v[34:37]
	v_mfma_f32_16x16x32_bf16 v[22:25], v[134:137], v[208:211], v[22:25]
	v_mfma_f32_16x16x32_bf16 v[18:21], v[170:173], v[208:211], v[18:21]
	v_mfma_f32_16x16x32_bf16 v[6:9], v[134:137], v[216:219], v[6:9]
	v_mfma_f32_16x16x32_bf16 v[2:5], v[170:173], v[216:219], v[2:5]
	s_setprio 0
	s_barrier
	s_add_u32 s11, s11, 0x100
	s_addc_u32 s19, s19, 0
	s_add_u32 s42, s42, 0x100
	s_addc_u32 s43, s43, 0
	s_cmp_ge_u32 s21, s96
	s_mov_b32 s20, s21
	s_cbranch_scc0 .LBB0_727
	s_and_b64 vcc, exec, s[30:31]
	s_cbranch_vccz .LBB0_730
	s_barrier
